# LN phases: rows on workgroups 0..423, weight conversion on 424..511 side by side
# baseline (speedup 1.0000x reference)
.LBB0_58:
	s_andn2_b64 vcc, exec, s[40:41]
	s_cbranch_vccnz .LBB0_145
	v_readlane_b32 s0, v254, 55
	v_lshl_add_u32 v0, s20, 8, v134
	s_cmp_lg_u32 s0, 3
	v_ashrrev_i32_e32 v130, 6, v0
	s_cselect_b64 s[40:41], -1, 0
	s_cmp_eq_u32 s0, 3
	s_mov_b32 s35, s16
	s_mov_b32 s25, s13
	v_lshlrev_b32_e32 v133, 2, v134
	s_cselect_b64 s[42:43], -1, 0
	s_cmp_eq_u32 s0, 3
	s_cbranch_scc1 .Lln_norole
	s_movk_i32 s34, 0x1a8
	s_cmp_lt_i32 s20, 0x1a8
	s_cbranch_scc1 .Lln_norole
	v_mov_b32_e32 v130, 0x7fffffff
.Lln_norole:
	v_cmp_gt_i32_e32 vcc, s14, v130
	s_and_saveexec_b64 s[16:17], vcc
	s_cbranch_execz .LBB0_104
	s_lshl_b32 s4, s34, 2
	s_add_u32 s18, s94, 0xfe40000
	v_readlane_b32 s10, v254, 55
	s_addc_u32 s19, s95, 0
	s_lshl_b32 s0, s10, 10
	s_ashr_i32 s1, s0, 31
	v_readlane_b32 s44, v253, 4
	s_lshl_b64 s[0:1], s[0:1], 2
	v_readlane_b32 s58, v253, 18
	v_readlane_b32 s59, v253, 19
	s_add_u32 s6, s58, s0
	v_and_b32_e32 v132, 0xfc, v133
	v_readlane_b32 s56, v253, 16
	s_addc_u32 s7, s59, s1
	v_readlane_b32 s57, v253, 17
	v_lshlrev_b32_e32 v0, 2, v132
	s_add_u32 s0, s56, s0
	s_addc_u32 s1, s57, s1
	global_load_dwordx4 v[2:5], v0, s[6:7] offset:3072
	global_load_dwordx4 v[6:9], v0, s[6:7] offset:2048
	global_load_dwordx4 v[10:13], v0, s[0:1] offset:3072
	global_load_dwordx4 v[14:17], v0, s[0:1] offset:2048
	global_load_dwordx4 v[18:21], v0, s[6:7] offset:1024
	global_load_dwordx4 v[22:25], v0, s[6:7]
	global_load_dwordx4 v[26:29], v0, s[0:1] offset:1024
	global_load_dwordx4 v[30:33], v0, s[0:1]
	s_mul_i32 s5, s10, 9
	s_add_i32 s6, s5, 9
	s_lshl_b32 s7, s34, 3
	s_add_u32 s8, s94, 0xea00000
	s_addc_u32 s9, s95, 0
	v_lshlrev_b32_e32 v0, 1, v132
	v_readlane_b32 s45, v253, 5
	v_readlane_b32 s48, v253, 8
	v_readlane_b32 s49, v253, 9
	s_cmp_eq_u32 s10, 0
	v_lshl_add_u64 v[34:35], s[94:95], 0, v[0:1]
	s_mov_b64 s[0:1], 0x4800000
	v_or_b32_e32 v136, 0x100, v132
	v_or_b32_e32 v138, 0x200, v132
	v_or_b32_e32 v140, 0x300, v132
	s_cselect_b32 s10, s49, s9
	s_cselect_b32 s11, s48, s8
	s_cselect_b32 s12, s45, s29
	s_cselect_b32 s13, s44, s28
	v_lshl_add_u64 v[142:143], v[34:35], 0, s[0:1]
	s_mov_b64 s[48:49], 0
	v_readlane_b32 s46, v253, 6
	v_readlane_b32 s47, v253, 7
	v_readlane_b32 s50, v253, 10
	v_readlane_b32 s51, v253, 11
	v_readlane_b32 s52, v253, 12
	v_readlane_b32 s53, v253, 13
	v_readlane_b32 s54, v253, 14
	v_readlane_b32 s55, v253, 15
	s_branch .LBB0_62

.LBB0_104:
	s_or_b64 exec, exec, s[16:17]
	s_and_b64 vcc, exec, s[40:41]
	v_readlane_b32 s11, v254, 54
	s_mov_b32 s10, 0x3d800000
	s_mov_b32 s13, s25
	s_mov_b32 s16, s35
	s_cbranch_vccz .LBB0_144
	s_and_b64 s[0:1], s[38:39], exec
	s_movk_i32 s0, 0x410
	s_cselect_b32 s4, s0, 0x500
	s_cmp_lt_i32 s20, 0x1a8
	s_cbranch_scc1 .LBB0_144
	s_sub_i32 s20, s20, 0x1a8
	s_sub_i32 s34, s76, 0x1a8
	s_cmp_ge_i32 s20, s4
	s_cbranch_scc1 .LBB0_144
	v_readlane_b32 s0, v254, 55
	s_add_i32 s0, s0, 1
	s_ashr_i32 s6, s0, 1
	s_ashr_i32 s7, s6, 31
	s_ashr_i32 s1, s0, 31
	s_lshl_b64 s[8:9], s[6:7], 17
	s_lshl_b64 s[10:11], s[0:1], 22
	s_lshl_b64 s[12:13], s[6:7], 24
	s_add_u32 s0, s94, 0xf200000
	s_addc_u32 s1, s95, 0
	s_add_u32 s5, s94, 0xfa00000
	v_readlane_b32 s40, v253, 20
	s_mul_hi_i32 s14, s6, 0xc00000
	s_mul_i32 s15, s6, 0xc00000
	s_addc_u32 s6, s95, 0
	v_readlane_b32 s52, v253, 32
	v_readlane_b32 s53, v253, 33
	s_add_u32 s12, s52, s12
	s_addc_u32 s13, s53, s13
	v_readlane_b32 s41, v253, 21
	s_add_u32 s10, s40, s10
	v_readlane_b32 s44, v253, 24
	s_addc_u32 s11, s41, s11
	v_readlane_b32 s45, v253, 25
	s_add_u32 s28, s44, s8
	v_readlane_b32 s42, v253, 22
	s_addc_u32 s29, s45, s9
	v_readlane_b32 s43, v253, 23
	v_lshlrev_b32_e32 v0, 2, v133
	s_add_u32 s8, s42, s15
	s_waitcnt vmcnt(0)
	v_and_b32_e32 v2, 0xf0, v0
	v_mov_b32_e32 v3, v1
	s_addc_u32 s9, s43, s14
	v_lshl_add_u64 v[4:5], s[12:13], 0, v[2:3]
	v_lshlrev_b32_e32 v0, 3, v134
	v_lshl_add_u64 v[6:7], s[10:11], 0, v[2:3]
	v_lshl_add_u64 v[8:9], s[8:9], 0, v[2:3]
	v_ashrrev_i32_e32 v3, 3, v134
	v_add_u32_e32 v10, 0x100, v134
	s_movk_i32 s7, 0x104
	v_and_b32_e32 v0, 56, v0
	v_ashrrev_i32_e32 v35, 3, v10
	v_lshlrev_b32_e32 v10, 2, v3
	v_mad_u32_u24 v36, v0, s7, v10
	v_lshlrev_b32_e32 v10, 2, v35
	v_mad_u32_u24 v37, v0, s7, v10
	v_max_i32_e32 v10, 0x1f00, v134
	v_sub_u32_e32 v10, v10, v134
	v_add_u32_e32 v10, 0xff, v10
	v_ashrrev_i32_e32 v30, 4, v134
	v_lshrrev_b32_e32 v11, 8, v10
	v_mul_lo_u32 v31, v30, s7
	v_add_u32_e32 v11, 1, v11
	v_and_b32_e32 v12, 0x300, v10
	s_movk_i32 s7, 0x300
	v_and_b32_e32 v11, 3, v11
	v_cmp_ne_u32_e64 s[40:41], s7, v12
	s_movk_i32 s7, 0x2ff
	v_add_u32_e32 v32, 16, v30
	v_add_u32_e32 v33, 32, v30
	v_add_u32_e32 v34, 48, v30
	v_cmp_gt_i32_e64 s[38:39], s37, v134
	v_cmp_lt_u32_e64 s[42:43], s7, v10
	v_sub_u32_e32 v38, 0, v11
	v_lshlrev_b32_e32 v10, 1, v0
	s_mov_b32 s7, s20
	v_readlane_b32 s46, v253, 26
	v_readlane_b32 s47, v253, 27
	v_readlane_b32 s48, v253, 28
	v_readlane_b32 s49, v253, 29
	v_readlane_b32 s50, v253, 30
	v_readlane_b32 s51, v253, 31
	v_readlane_b32 s54, v253, 34
	v_readlane_b32 s55, v253, 35
	s_branch .LBB0_108
